# nt cache policy on the never-re-read final output stores of the last GEMM phase epilogue, stacked on v82
# baseline (speedup 1.0000x reference)
; __device__ __forceinline__ float bf2f(unsigned b) { return __uint_as_float(b << 16); }
; #define EPI_GET(dst, ai, bj, m, s) do { _Pragma("unroll") for (int e_ = 0; e_ < 4; ++e_) { (dst)[e_] = acc[ai][bj][m][0][e_] * (s); (dst)[4 + e_] = acc[ai][bj][m][1][e_] * (s); } } while (0)
;     __device__ __forceinline__ void row(const f32x4 (&acc)[2][2][4][2], int ai, int m, int r, int rl, bool samp, int c8, int fq, const float* a, const float* b) const {
;         float lo[8], hi[8]; EPI_GET(lo, ai, 0, m, 1.f); EPI_GET(hi, ai, 1, m, 1.f);
;         float s2 = 0.f;
; #pragma unroll
;         for (int e = 0; e < 8; ++e) { lo[e] += a[e]; hi[e] += b[e]; s2 += lo[e] * lo[e] + hi[e] * hi[e]; }
;         if (dstP) { float* dp = (samp ? dstS : dstP) + (size_t)rl * 1024 + c8; store8_f32(dp, lo); store8_f32(dp + 128, hi); }
;         if (dstB) { store8_bf16(dstB + (size_t)r * 1024 + c8, lo); store8_bf16(dstB + (size_t)r * 1024 + c8 + 128, hi); }
;         if (ss) { s2 += __shfl_xor(s2, 16); s2 += __shfl_xor(s2, 32); if (fq == 0) atomicAdd(ss + r, s2); }
;     }
;     __device__ __forceinline__ void operator()(const f32x4 (&acc)[2][2][4][2], const Unit& u, int wr, int wc, int fr, int fq) const {
;         const bool samp = (u.pm >= 64); const int c8 = u.pn * 256 + wc * 32 + 8 * fq;
;         if (resB) {
; #pragma unroll
;             for (int ai = 0; ai < 2; ++ai) {
;                 u32x4 ra[4], rb[4];
; #pragma unroll
;                 for (int m = 0; m < 4; ++m) { const int r = EPI_ROWS(ai, m); ra[m] = *(const u32x4*)(resB + (size_t)r * 1024 + c8); rb[m] = *(const u32x4*)(resB + (size_t)r * 1024 + c8 + 128); }
; #pragma unroll
;                 for (int m = 0; m < 4; ++m) { const int r = EPI_ROWS(ai, m); const int rl = samp ? r - MP : r; float a[8], b[8];
;                     const u32x4 wa = ra[m], wb = rb[m];
;                     a[0] = bf2f(wa.x & 0xffffu); a[1] = bf2f(wa.x >> 16); a[2] = bf2f(wa.y & 0xffffu); a[3] = bf2f(wa.y >> 16); a[4] = bf2f(wa.z & 0xffffu); a[5] = bf2f(wa.z >> 16); a[6] = bf2f(wa.w & 0xffffu); a[7] = bf2f(wa.w >> 16);
;                     b[0] = bf2f(wb.x & 0xffffu); b[1] = bf2f(wb.x >> 16); b[2] = bf2f(wb.y & 0xffffu); b[3] = bf2f(wb.y >> 16); b[4] = bf2f(wb.z & 0xffffu); b[5] = bf2f(wb.z >> 16); b[6] = bf2f(wb.w & 0xffffu); b[7] = bf2f(wb.w >> 16);
;                     row(acc, ai, m, r, rl, samp, c8, fq, a, b); }
.LBB0_3619:
	s_andn2_b64 vcc, exec, s[16:17]
	s_cbranch_vccnz .LBB0_3621
	v_lshl_add_u32 v146, s46, 8, v154
	v_lshl_add_u32 v144, s45, 8, v152
	v_ashrrev_i32_e32 v147, 31, v146
	v_ashrrev_i32_e32 v145, 31, v144
	v_lshl_add_u64 v[148:149], v[146:147], 1, s[6:7]
	v_lshlrev_b64 v[150:151], 11, v[144:145]
	v_or_b32_e32 v182, 16, v144
	v_lshl_add_u64 v[150:151], v[148:149], 0, v[150:151]
	v_ashrrev_i32_e32 v183, 31, v182
	global_load_dwordx4 v[158:161], v[150:151], off
	global_load_dwordx4 v[162:165], v[150:151], off offset:256
	v_lshlrev_b64 v[150:151], 11, v[182:183]
	v_lshl_add_u64 v[150:151], v[148:149], 0, v[150:151]
	global_load_dwordx4 v[166:169], v[150:151], off
	global_load_dwordx4 v[170:173], v[150:151], off offset:256
	v_or_b32_e32 v190, 32, v144
	v_ashrrev_i32_e32 v191, 31, v190
	v_lshlrev_b64 v[174:175], 11, v[190:191]
	v_lshl_add_u64 v[178:179], v[148:149], 0, v[174:175]
	global_load_dwordx4 v[174:177], v[178:179], off offset:256
	s_nop 0
	global_load_dwordx4 v[178:181], v[178:179], off
	s_cmp_gt_i32 s45, 63
	v_or_b32_e32 v150, 48, v144
	v_add_u32_e32 v145, 0xffffc000, v144
	v_add_u32_e32 v183, 0xffffc010, v144
	v_ashrrev_i32_e32 v151, 31, v150
	s_cselect_b64 vcc, -1, 0
	v_cndmask_b32_e32 v184, v144, v145, vcc
	v_cndmask_b32_e32 v182, v182, v183, vcc
	v_lshlrev_b64 v[186:187], 11, v[150:151]
	v_ashrrev_i32_e32 v185, 31, v184
	v_ashrrev_i32_e32 v183, 31, v182
	v_lshl_add_u64 v[186:187], v[148:149], 0, v[186:187]
	v_lshlrev_b64 v[192:193], 12, v[184:185]
	v_lshlrev_b64 v[194:195], 12, v[182:183]
	global_load_dwordx4 v[182:185], v[186:187], off offset:256
	s_nop 0
	global_load_dwordx4 v[186:189], v[186:187], off
	s_and_b64 s[20:21], vcc, exec
	v_readlane_b32 s20, v250, 0
	v_readlane_b32 s21, v250, 1
	v_readlane_b32 s22, v250, 2
	v_readlane_b32 s23, v250, 3
	s_cselect_b32 s21, s9, s23
	s_cselect_b32 s20, s8, s22
	v_lshlrev_b64 v[146:147], 2, v[146:147]
	v_lshl_add_u64 v[192:193], s[20:21], 0, v[192:193]
	v_lshl_add_u64 v[192:193], v[192:193], 0, v[146:147]
	v_lshl_add_u64 v[194:195], s[20:21], 0, v[194:195]
	v_lshl_add_u64 v[194:195], v[194:195], 0, v[146:147]
	v_readlane_b32 s24, v250, 4
	v_readlane_b32 s25, v250, 5
	v_readlane_b32 s26, v250, 6
	v_readlane_b32 s27, v250, 7
	s_waitcnt vmcnt(0)
	v_lshlrev_b32_e32 v198, 16, v158
	v_and_b32_e32 v199, 0xffff0000, v158
	v_lshlrev_b32_e32 v158, 16, v159
	v_and_b32_e32 v159, 0xffff0000, v159
	v_lshlrev_b32_e32 v200, 16, v164
	v_and_b32_e32 v201, 0xffff0000, v164
	v_lshlrev_b32_e32 v196, 16, v160
	v_and_b32_e32 v197, 0xffff0000, v160
	v_lshlrev_b32_e32 v160, 16, v161
	v_and_b32_e32 v161, 0xffff0000, v161
	v_lshlrev_b32_e32 v164, 16, v165
	v_and_b32_e32 v165, 0xffff0000, v165
	v_lshlrev_b32_e32 v202, 16, v162
	v_and_b32_e32 v203, 0xffff0000, v162
	v_lshlrev_b32_e32 v162, 16, v163
	v_and_b32_e32 v163, 0xffff0000, v163
	v_pk_add_f32 v[124:125], v[124:125], v[198:199]
	v_pk_add_f32 v[126:127], v[126:127], v[158:159]
	v_pk_add_f32 v[112:113], v[112:113], v[200:201]
	v_pk_add_f32 v[120:121], v[120:121], v[196:197]
	v_pk_add_f32 v[122:123], v[122:123], v[160:161]
	v_pk_add_f32 v[114:115], v[114:115], v[164:165]
	v_pk_add_f32 v[116:117], v[116:117], v[202:203]
	v_pk_add_f32 v[118:119], v[118:119], v[162:163]
	global_store_dwordx4 v[192:193], v[124:127], off nt
	global_store_dwordx4 v[192:193], v[120:123], off offset:16 nt
	global_store_dwordx4 v[192:193], v[116:119], off offset:512 nt
	global_store_dwordx4 v[192:193], v[112:115], off offset:528 nt
	v_lshlrev_b32_e32 v162, 16, v166
	v_and_b32_e32 v163, 0xffff0000, v166
	v_lshlrev_b32_e32 v112, 16, v173
	v_and_b32_e32 v113, 0xffff0000, v173
	v_pk_add_f32 v[102:103], v[102:103], v[112:113]
	v_lshlrev_b32_e32 v112, 16, v170
	v_and_b32_e32 v113, 0xffff0000, v170
	v_lshlrev_b32_e32 v164, 16, v167
	v_and_b32_e32 v165, 0xffff0000, v167
	v_pk_add_f32 v[96:97], v[96:97], v[112:113]
	v_lshlrev_b32_e32 v112, 16, v171
	v_and_b32_e32 v113, 0xffff0000, v171
	v_lshlrev_b32_e32 v158, 16, v168
	v_and_b32_e32 v159, 0xffff0000, v168
	v_lshlrev_b32_e32 v160, 16, v169
	v_and_b32_e32 v161, 0xffff0000, v169
	v_lshlrev_b32_e32 v166, 16, v172
	v_and_b32_e32 v167, 0xffff0000, v172
	v_pk_add_f32 v[108:109], v[108:109], v[162:163]
	v_pk_add_f32 v[110:111], v[110:111], v[164:165]
	v_pk_add_f32 v[98:99], v[98:99], v[112:113]
	v_pk_add_f32 v[104:105], v[104:105], v[158:159]
	v_pk_add_f32 v[106:107], v[106:107], v[160:161]
	v_pk_add_f32 v[100:101], v[100:101], v[166:167]
	global_store_dwordx4 v[194:195], v[108:111], off nt
	global_store_dwordx4 v[194:195], v[104:107], off offset:16 nt
	global_store_dwordx4 v[194:195], v[96:99], off offset:512 nt
	global_store_dwordx4 v[194:195], v[100:103], off offset:528 nt
	s_nop 0
	v_lshlrev_b32_e32 v98, 16, v180
	v_and_b32_e32 v99, 0xffff0000, v180
	v_pk_add_f32 v[92:93], v[92:93], v[98:99]
	v_lshlrev_b32_e32 v98, 16, v181
	v_and_b32_e32 v99, 0xffff0000, v181
	v_pk_add_f32 v[94:95], v[94:95], v[98:99]
	v_lshlrev_b32_e32 v98, 16, v178
	v_and_b32_e32 v99, 0xffff0000, v178
	v_add_u32_e32 v96, 0xffffc020, v144
	v_pk_add_f32 v[88:89], v[88:89], v[98:99]
	v_lshlrev_b32_e32 v98, 16, v179
	v_and_b32_e32 v99, 0xffff0000, v179
	v_cndmask_b32_e32 v96, v190, v96, vcc
	v_pk_add_f32 v[90:91], v[90:91], v[98:99]
	v_lshlrev_b32_e32 v98, 16, v176
	v_and_b32_e32 v99, 0xffff0000, v176
	v_ashrrev_i32_e32 v97, 31, v96
	v_pk_add_f32 v[84:85], v[84:85], v[98:99]
	v_lshlrev_b32_e32 v98, 16, v177
	v_and_b32_e32 v99, 0xffff0000, v177
	v_lshlrev_b64 v[96:97], 12, v[96:97]
	v_pk_add_f32 v[86:87], v[86:87], v[98:99]
	v_lshlrev_b32_e32 v98, 16, v174
	v_and_b32_e32 v99, 0xffff0000, v174
	v_lshl_add_u64 v[96:97], s[20:21], 0, v[96:97]
	v_pk_add_f32 v[80:81], v[80:81], v[98:99]
; __device__ __forceinline__ float bf2f(unsigned b) { return __uint_as_float(b << 16); }
; #define EPI_GET(dst, ai, bj, m, s) do { _Pragma("unroll") for (int e_ = 0; e_ < 4; ++e_) { (dst)[e_] = acc[ai][bj][m][0][e_] * (s); (dst)[4 + e_] = acc[ai][bj][m][1][e_] * (s); } } while (0)
;     __device__ __forceinline__ void row(const f32x4 (&acc)[2][2][4][2], int ai, int m, int r, int rl, bool samp, int c8, int fq, const float* a, const float* b) const {
;         float lo[8], hi[8]; EPI_GET(lo, ai, 0, m, 1.f); EPI_GET(hi, ai, 1, m, 1.f);
;         float s2 = 0.f;
; #pragma unroll
;         for (int e = 0; e < 8; ++e) { lo[e] += a[e]; hi[e] += b[e]; s2 += lo[e] * lo[e] + hi[e] * hi[e]; }
;         if (dstP) { float* dp = (samp ? dstS : dstP) + (size_t)rl * 1024 + c8; store8_f32(dp, lo); store8_f32(dp + 128, hi); }
;         if (dstB) { store8_bf16(dstB + (size_t)r * 1024 + c8, lo); store8_bf16(dstB + (size_t)r * 1024 + c8 + 128, hi); }
;         if (ss) { s2 += __shfl_xor(s2, 16); s2 += __shfl_xor(s2, 32); if (fq == 0) atomicAdd(ss + r, s2); }
;     }
;     __device__ __forceinline__ void operator()(const f32x4 (&acc)[2][2][4][2], const Unit& u, int wr, int wc, int fr, int fq) const {
;         const bool samp = (u.pm >= 64); const int c8 = u.pn * 256 + wc * 32 + 8 * fq;
;         if (resB) {
; #pragma unroll
;             for (int ai = 0; ai < 2; ++ai) {
;                 u32x4 ra[4], rb[4];
; #pragma unroll
;                 for (int m = 0; m < 4; ++m) { const int r = EPI_ROWS(ai, m); ra[m] = *(const u32x4*)(resB + (size_t)r * 1024 + c8); rb[m] = *(const u32x4*)(resB + (size_t)r * 1024 + c8 + 128); }
; #pragma unroll
;                 for (int m = 0; m < 4; ++m) { const int r = EPI_ROWS(ai, m); const int rl = samp ? r - MP : r; float a[8], b[8];
;                     const u32x4 wa = ra[m], wb = rb[m];
;                     a[0] = bf2f(wa.x & 0xffffu); a[1] = bf2f(wa.x >> 16); a[2] = bf2f(wa.y & 0xffffu); a[3] = bf2f(wa.y >> 16); a[4] = bf2f(wa.z & 0xffffu); a[5] = bf2f(wa.z >> 16); a[6] = bf2f(wa.w & 0xffffu); a[7] = bf2f(wa.w >> 16);
;                     b[0] = bf2f(wb.x & 0xffffu); b[1] = bf2f(wb.x >> 16); b[2] = bf2f(wb.y & 0xffffu); b[3] = bf2f(wb.y >> 16); b[4] = bf2f(wb.z & 0xffffu); b[5] = bf2f(wb.z >> 16); b[6] = bf2f(wb.w & 0xffffu); b[7] = bf2f(wb.w >> 16);
;                     row(acc, ai, m, r, rl, samp, c8, fq, a, b); }
	v_lshlrev_b32_e32 v98, 16, v175
	v_and_b32_e32 v99, 0xffff0000, v175
	v_lshl_add_u64 v[96:97], v[96:97], 0, v[146:147]
	v_pk_add_f32 v[82:83], v[82:83], v[98:99]
	global_store_dwordx4 v[96:97], v[88:91], off nt
	global_store_dwordx4 v[96:97], v[92:95], off offset:16 nt
	global_store_dwordx4 v[96:97], v[80:83], off offset:512 nt
	global_store_dwordx4 v[96:97], v[84:87], off offset:528 nt
	v_add_u32_e32 v96, 0x80, v144
	v_lshlrev_b32_e32 v82, 16, v188
	v_and_b32_e32 v83, 0xffff0000, v188
	v_pk_add_f32 v[76:77], v[76:77], v[82:83]
	v_lshlrev_b32_e32 v82, 16, v189
	v_and_b32_e32 v83, 0xffff0000, v189
	v_add_u32_e32 v80, 0xffffc030, v144
	v_pk_add_f32 v[78:79], v[78:79], v[82:83]
	v_lshlrev_b32_e32 v82, 16, v186
	v_and_b32_e32 v83, 0xffff0000, v186
	v_cndmask_b32_e32 v80, v150, v80, vcc
	v_pk_add_f32 v[72:73], v[72:73], v[82:83]
	v_lshlrev_b32_e32 v82, 16, v187
	v_and_b32_e32 v83, 0xffff0000, v187
	v_ashrrev_i32_e32 v81, 31, v80
	v_pk_add_f32 v[74:75], v[74:75], v[82:83]
	v_lshlrev_b32_e32 v82, 16, v184
	v_and_b32_e32 v83, 0xffff0000, v184
	v_lshlrev_b64 v[80:81], 12, v[80:81]
	v_pk_add_f32 v[68:69], v[68:69], v[82:83]
	v_lshlrev_b32_e32 v82, 16, v185
	v_and_b32_e32 v83, 0xffff0000, v185
	v_lshl_add_u64 v[80:81], s[20:21], 0, v[80:81]
	v_pk_add_f32 v[70:71], v[70:71], v[82:83]
	v_lshlrev_b32_e32 v82, 16, v182
	v_and_b32_e32 v83, 0xffff0000, v182
	v_lshl_add_u64 v[80:81], v[80:81], 0, v[146:147]
	v_pk_add_f32 v[64:65], v[64:65], v[82:83]
	v_lshlrev_b32_e32 v82, 16, v183
	v_and_b32_e32 v83, 0xffff0000, v183
	v_ashrrev_i32_e32 v97, 31, v96
	v_pk_add_f32 v[66:67], v[66:67], v[82:83]
	global_store_dwordx4 v[80:81], v[72:75], off nt
	global_store_dwordx4 v[80:81], v[76:79], off offset:16 nt
	global_store_dwordx4 v[80:81], v[64:67], off offset:512 nt
	global_store_dwordx4 v[80:81], v[68:71], off offset:528 nt
	v_add_u32_e32 v98, 0x90, v144
	v_lshlrev_b64 v[64:65], 11, v[96:97]
	v_lshl_add_u64 v[64:65], v[148:149], 0, v[64:65]
	global_load_dwordx4 v[68:71], v[64:65], off
	global_load_dwordx4 v[72:75], v[64:65], off offset:256
	v_ashrrev_i32_e32 v99, 31, v98
	v_lshlrev_b64 v[64:65], 11, v[98:99]
	v_lshl_add_u64 v[64:65], v[148:149], 0, v[64:65]
	global_load_dwordx4 v[76:79], v[64:65], off
	global_load_dwordx4 v[80:83], v[64:65], off offset:256
	v_add_u32_e32 v102, 0xa0, v144
	v_ashrrev_i32_e32 v103, 31, v102
	v_lshlrev_b64 v[64:65], 11, v[102:103]
	v_lshl_add_u64 v[64:65], v[148:149], 0, v[64:65]
	global_load_dwordx4 v[84:87], v[64:65], off offset:256
	global_load_dwordx4 v[88:91], v[64:65], off
	v_add_u32_e32 v100, 0xb0, v144
	v_ashrrev_i32_e32 v101, 31, v100
	v_lshlrev_b64 v[64:65], 11, v[100:101]
	v_lshl_add_u64 v[104:105], v[148:149], 0, v[64:65]
	global_load_dwordx4 v[64:67], v[104:105], off offset:256
	global_load_dwordx4 v[92:95], v[104:105], off
	v_add_u32_e32 v97, 0xffffc080, v144
	v_cndmask_b32_e32 v96, v96, v97, vcc
	v_ashrrev_i32_e32 v97, 31, v96
	v_lshlrev_b64 v[96:97], 12, v[96:97]
	v_lshl_add_u64 v[96:97], s[20:21], 0, v[96:97]
	v_lshl_add_u64 v[96:97], v[96:97], 0, v[146:147]
	s_waitcnt vmcnt(7)
	v_lshlrev_b32_e32 v104, 16, v70
	v_and_b32_e32 v105, 0xffff0000, v70
	v_lshlrev_b32_e32 v70, 16, v71
	v_and_b32_e32 v71, 0xffff0000, v71
	v_pk_add_f32 v[62:63], v[62:63], v[70:71]
	v_lshlrev_b32_e32 v70, 16, v68
	v_and_b32_e32 v71, 0xffff0000, v68
	v_lshlrev_b32_e32 v68, 16, v69
	v_and_b32_e32 v69, 0xffff0000, v69
	v_pk_add_f32 v[58:59], v[58:59], v[68:69]
	s_waitcnt vmcnt(6)
	v_lshlrev_b32_e32 v68, 16, v74
	v_and_b32_e32 v69, 0xffff0000, v74
	v_pk_add_f32 v[52:53], v[52:53], v[68:69]
	v_lshlrev_b32_e32 v68, 16, v75
	v_and_b32_e32 v69, 0xffff0000, v75
	v_pk_add_f32 v[54:55], v[54:55], v[68:69]
	v_lshlrev_b32_e32 v68, 16, v72
	v_and_b32_e32 v69, 0xffff0000, v72
	v_pk_add_f32 v[48:49], v[48:49], v[68:69]
	v_lshlrev_b32_e32 v68, 16, v73
	v_and_b32_e32 v69, 0xffff0000, v73
	v_pk_add_f32 v[56:57], v[56:57], v[70:71]
	v_pk_add_f32 v[50:51], v[50:51], v[68:69]
	v_pk_add_f32 v[60:61], v[60:61], v[104:105]
	global_store_dwordx4 v[96:97], v[56:59], off nt
	global_store_dwordx4 v[96:97], v[60:63], off offset:16 nt
	global_store_dwordx4 v[96:97], v[48:51], off offset:512 nt
	global_store_dwordx4 v[96:97], v[52:55], off offset:528 nt
	s_waitcnt vmcnt(9)
; __device__ __forceinline__ float bf2f(unsigned b) { return __uint_as_float(b << 16); }
; #define EPI_GET(dst, ai, bj, m, s) do { _Pragma("unroll") for (int e_ = 0; e_ < 4; ++e_) { (dst)[e_] = acc[ai][bj][m][0][e_] * (s); (dst)[4 + e_] = acc[ai][bj][m][1][e_] * (s); } } while (0)
;     __device__ __forceinline__ void row(const f32x4 (&acc)[2][2][4][2], int ai, int m, int r, int rl, bool samp, int c8, int fq, const float* a, const float* b) const {
;         float lo[8], hi[8]; EPI_GET(lo, ai, 0, m, 1.f); EPI_GET(hi, ai, 1, m, 1.f);
;         float s2 = 0.f;
; #pragma unroll
;         for (int e = 0; e < 8; ++e) { lo[e] += a[e]; hi[e] += b[e]; s2 += lo[e] * lo[e] + hi[e] * hi[e]; }
;         if (dstP) { float* dp = (samp ? dstS : dstP) + (size_t)rl * 1024 + c8; store8_f32(dp, lo); store8_f32(dp + 128, hi); }
;         if (dstB) { store8_bf16(dstB + (size_t)r * 1024 + c8, lo); store8_bf16(dstB + (size_t)r * 1024 + c8 + 128, hi); }
;         if (ss) { s2 += __shfl_xor(s2, 16); s2 += __shfl_xor(s2, 32); if (fq == 0) atomicAdd(ss + r, s2); }
;     }
;     __device__ __forceinline__ void operator()(const f32x4 (&acc)[2][2][4][2], const Unit& u, int wr, int wc, int fr, int fq) const {
;         const bool samp = (u.pm >= 64); const int c8 = u.pn * 256 + wc * 32 + 8 * fq;
;         if (resB) {
; #pragma unroll
;             for (int ai = 0; ai < 2; ++ai) {
;                 u32x4 ra[4], rb[4];
; #pragma unroll
;                 for (int m = 0; m < 4; ++m) { const int r = EPI_ROWS(ai, m); ra[m] = *(const u32x4*)(resB + (size_t)r * 1024 + c8); rb[m] = *(const u32x4*)(resB + (size_t)r * 1024 + c8 + 128); }
; #pragma unroll
;                 for (int m = 0; m < 4; ++m) { const int r = EPI_ROWS(ai, m); const int rl = samp ? r - MP : r; float a[8], b[8];
;                     const u32x4 wa = ra[m], wb = rb[m];
;                     a[0] = bf2f(wa.x & 0xffffu); a[1] = bf2f(wa.x >> 16); a[2] = bf2f(wa.y & 0xffffu); a[3] = bf2f(wa.y >> 16); a[4] = bf2f(wa.z & 0xffffu); a[5] = bf2f(wa.z >> 16); a[6] = bf2f(wa.w & 0xffffu); a[7] = bf2f(wa.w >> 16);
;                     b[0] = bf2f(wb.x & 0xffffu); b[1] = bf2f(wb.x >> 16); b[2] = bf2f(wb.y & 0xffffu); b[3] = bf2f(wb.y >> 16); b[4] = bf2f(wb.z & 0xffffu); b[5] = bf2f(wb.z >> 16); b[6] = bf2f(wb.w & 0xffffu); b[7] = bf2f(wb.w >> 16);
;                     row(acc, ai, m, r, rl, samp, c8, fq, a, b); }
	v_lshlrev_b32_e32 v50, 16, v78
	v_and_b32_e32 v51, 0xffff0000, v78
	v_pk_add_f32 v[44:45], v[44:45], v[50:51]
	v_lshlrev_b32_e32 v50, 16, v79
	v_and_b32_e32 v51, 0xffff0000, v79
	v_pk_add_f32 v[46:47], v[46:47], v[50:51]
	v_lshlrev_b32_e32 v50, 16, v76
	v_and_b32_e32 v51, 0xffff0000, v76
	v_add_u32_e32 v48, 0xffffc090, v144
	v_pk_add_f32 v[40:41], v[40:41], v[50:51]
	v_lshlrev_b32_e32 v50, 16, v77
	v_and_b32_e32 v51, 0xffff0000, v77
	v_cndmask_b32_e32 v48, v98, v48, vcc
	v_pk_add_f32 v[42:43], v[42:43], v[50:51]
	s_waitcnt vmcnt(8)
	v_lshlrev_b32_e32 v50, 16, v82
	v_and_b32_e32 v51, 0xffff0000, v82
	v_ashrrev_i32_e32 v49, 31, v48
	v_pk_add_f32 v[36:37], v[36:37], v[50:51]
	v_lshlrev_b32_e32 v50, 16, v83
	v_and_b32_e32 v51, 0xffff0000, v83
	v_lshlrev_b64 v[48:49], 12, v[48:49]
	v_pk_add_f32 v[38:39], v[38:39], v[50:51]
	v_lshlrev_b32_e32 v50, 16, v80
	v_and_b32_e32 v51, 0xffff0000, v80
	v_lshl_add_u64 v[48:49], s[20:21], 0, v[48:49]
	v_pk_add_f32 v[32:33], v[32:33], v[50:51]
	v_lshlrev_b32_e32 v50, 16, v81
	v_and_b32_e32 v51, 0xffff0000, v81
	v_lshl_add_u64 v[48:49], v[48:49], 0, v[146:147]
	v_pk_add_f32 v[34:35], v[34:35], v[50:51]
	global_store_dwordx4 v[48:49], v[40:43], off nt
	global_store_dwordx4 v[48:49], v[44:47], off offset:16 nt
	global_store_dwordx4 v[48:49], v[32:35], off offset:512 nt
	global_store_dwordx4 v[48:49], v[36:39], off offset:528 nt
	s_waitcnt vmcnt(10)
	v_lshlrev_b32_e32 v34, 16, v90
	v_and_b32_e32 v35, 0xffff0000, v90
	v_pk_add_f32 v[28:29], v[28:29], v[34:35]
	v_lshlrev_b32_e32 v34, 16, v91
	v_and_b32_e32 v35, 0xffff0000, v91
	v_pk_add_f32 v[30:31], v[30:31], v[34:35]
	v_lshlrev_b32_e32 v34, 16, v88
	v_and_b32_e32 v35, 0xffff0000, v88
	v_add_u32_e32 v32, 0xffffc0a0, v144
	v_pk_add_f32 v[24:25], v[24:25], v[34:35]
	v_lshlrev_b32_e32 v34, 16, v89
	v_and_b32_e32 v35, 0xffff0000, v89
	v_cndmask_b32_e32 v32, v102, v32, vcc
	v_pk_add_f32 v[26:27], v[26:27], v[34:35]
	v_lshlrev_b32_e32 v34, 16, v86
	v_and_b32_e32 v35, 0xffff0000, v86
	v_ashrrev_i32_e32 v33, 31, v32
	v_pk_add_f32 v[20:21], v[20:21], v[34:35]
	v_lshlrev_b32_e32 v34, 16, v87
	v_and_b32_e32 v35, 0xffff0000, v87
	v_lshlrev_b64 v[32:33], 12, v[32:33]
	v_pk_add_f32 v[22:23], v[22:23], v[34:35]
	v_lshlrev_b32_e32 v34, 16, v84
	v_and_b32_e32 v35, 0xffff0000, v84
	v_lshl_add_u64 v[32:33], s[20:21], 0, v[32:33]
	v_pk_add_f32 v[16:17], v[16:17], v[34:35]
	v_lshlrev_b32_e32 v34, 16, v85
	v_and_b32_e32 v35, 0xffff0000, v85
	v_lshl_add_u64 v[32:33], v[32:33], 0, v[146:147]
	v_pk_add_f32 v[18:19], v[18:19], v[34:35]
	global_store_dwordx4 v[32:33], v[24:27], off nt
	global_store_dwordx4 v[32:33], v[28:31], off offset:16 nt
	global_store_dwordx4 v[32:33], v[16:19], off offset:512 nt
	global_store_dwordx4 v[32:33], v[20:23], off offset:528 nt
	s_waitcnt vmcnt(12)
	v_lshlrev_b32_e32 v18, 16, v94
	v_and_b32_e32 v19, 0xffff0000, v94
	v_pk_add_f32 v[12:13], v[12:13], v[18:19]
	v_lshlrev_b32_e32 v18, 16, v95
	v_and_b32_e32 v19, 0xffff0000, v95
	v_add_u32_e32 v16, 0xffffc0b0, v144
	v_pk_add_f32 v[14:15], v[14:15], v[18:19]
	v_lshlrev_b32_e32 v18, 16, v92
	v_and_b32_e32 v19, 0xffff0000, v92
	v_cndmask_b32_e32 v16, v100, v16, vcc
	v_pk_add_f32 v[8:9], v[8:9], v[18:19]
	v_lshlrev_b32_e32 v18, 16, v93
	v_and_b32_e32 v19, 0xffff0000, v93
	v_ashrrev_i32_e32 v17, 31, v16
	v_pk_add_f32 v[10:11], v[10:11], v[18:19]
	v_lshlrev_b32_e32 v18, 16, v66
	v_and_b32_e32 v19, 0xffff0000, v66
	v_lshlrev_b64 v[16:17], 12, v[16:17]
	v_pk_add_f32 v[4:5], v[4:5], v[18:19]
	v_lshlrev_b32_e32 v18, 16, v67
	v_and_b32_e32 v19, 0xffff0000, v67
	v_lshl_add_u64 v[16:17], s[20:21], 0, v[16:17]
	v_pk_add_f32 v[6:7], v[6:7], v[18:19]
	v_lshlrev_b32_e32 v18, 16, v64
	v_and_b32_e32 v19, 0xffff0000, v64
	v_lshl_add_u64 v[16:17], v[16:17], 0, v[146:147]
	v_pk_add_f32 v[0:1], v[0:1], v[18:19]
	v_lshlrev_b32_e32 v18, 16, v65
	v_and_b32_e32 v19, 0xffff0000, v65
	v_pk_add_f32 v[2:3], v[2:3], v[18:19]
	global_store_dwordx4 v[16:17], v[8:11], off nt
	global_store_dwordx4 v[16:17], v[12:15], off offset:16 nt
	global_store_dwordx4 v[16:17], v[0:3], off offset:512 nt
	global_store_dwordx4 v[16:17], v[4:7], off offset:528 nt
